# speedup vs baseline: 1.0280x; 1.0008x over previous
; template <int MODE> ...
;     ...
;   const int tid = opaque_tid(), lane = tid & 63, w = tid >> 6;
;   const int g = lane >> 5, ql = lane & 31;
;   const int t_q = qt * 256 + w * 32 + ql;
;   const int w_first = qt * 256 + w * 32, w_last = w_first + 31;
;   const size_t row_q = (size_t)b * LP + t_q;
;   char* Ks = smem;
;   char* Vs = smem + KSZ;
;   int* flags = reinterpret_cast<int*>(smem + MISC_OFF + 64);
;   bf16x8 qf[NKS];
;   {
;     const bf16_t* qsrc = Qg + row_q * QLD + h * QHD + g * 8;
; #pragma unroll
;     for (int ks = 0; ks < NKS; ++ks) qf[ks] = *reinterpret_cast<const bf16x8*>(qsrc + ks * 16);
;   }
;   f32x16 O[4];
; #pragma unroll
;   for (int mb = 0; mb < 4; ++mb)
; #pragma unroll
;     for (int i = 0; i < 16; ++i) O[mb][i] = 0.f;
;   float m_run = -1e30f, l_run = 0.f, carry = 0.f;
;   const int c8 = tid & 7, kr_ = tid >> 3;
;   const int vc = tid & 7, vd = tid >> 3;
;   const bf16_t* k1p = K1g + ((size_t)b * LP + kr_) * 1024 + h * 128 + c8 * 8;
;   const bf16_t* k2p = K2g + ((size_t)b * LP + kr_) * 64 + c8 * 8;
;   const bf16_t* vp0 = VTg + ((size_t)(b * 8 + h) * 128 + vd) * LP + vc * 8;
;   const int ks_off = (c8 * 65 + kr_) * 16;
;   const int vs_off = vd * 136 + vc * 16;
;   uint4 k0, k1, k2, v0, v1;
;   k2 = make_uint4(0u, 0u, 0u, 0u);
;     ...
;   const int kt_hi = (4 * qt + 3 < (L - 1) / 64) ? (4 * qt + 3) : ((L - 1) / 64);
;   LOAD_KV(kt_hi);
;   __syncthreads();
;   STORE_KV(0);
;   LOAD_KV(kt_hi - 1);
;   __syncthreads();
.LBB0_347:
	s_waitcnt vmcnt(2)
	v_mov_b32_e32 v4, v252
	s_ashr_i32 s6, s59, 4
	s_sub_i32 s8, 32, s6
	v_ashrrev_i32_e32 v0, 1, v4
	v_and_b32_e32 v0, 0xffffffe0, v0
	v_and_b32_e32 v43, 31, v4
	v_lshl_add_u32 v166, s8, 8, v0
	s_bfe_u32 s9, s59, 0x10003
	v_or_b32_e32 v30, v166, v43
	s_mul_i32 s74, s9, 0x2010
	v_ashrrev_i32_e32 v31, 31, v30
	v_lshl_add_u64 v[154:155], v[30:31], 0, s[74:75]
	v_mov_b64_e32 v[2:3], s[52:53]
	s_movk_i32 s11, 0xc00
	s_and_b32 s10, s59, 7
	v_mad_u64_u32 v[2:3], s[6:7], v154, s11, v[2:3]
	v_mad_i32_i24 v3, v155, s11, v3
	s_mul_i32 s6, s10, 0x180
	s_mov_b32 s7, s75
	v_lshl_add_u64 v[2:3], v[2:3], 0, s[6:7]
	s_load_dwordx2 s[6:7], s[96:97], 0x118
	v_bfe_u32 v42, v4, 5, 1
	v_ashrrev_i32_e32 v38, 3, v4
	v_lshlrev_b32_e32 v0, 4, v42
	v_ashrrev_i32_e32 v39, 31, v38
	v_lshl_add_u64 v[36:37], v[2:3], 0, v[0:1]
	v_lshl_add_u64 v[2:3], v[38:39], 0, s[74:75]
	v_and_b32_e32 v31, 7, v4
	v_lshlrev_b64 v[4:5], 11, v[2:3]
	v_lshlrev_b64 v[2:3], 7, v[2:3]
	v_lshl_add_u64 v[4:5], s[54:55], 0, v[4:5]
	s_lshl_b32 s12, s10, 7
	s_lshl_b32 s74, s10, 8
	s_waitcnt lgkmcnt(0)
	v_lshl_add_u64 v[2:3], s[6:7], 0, v[2:3]
	s_lshl_b32 s6, s9, 10
	v_lshl_add_u64 v[4:5], v[4:5], 0, s[74:75]
	v_lshlrev_b32_e32 v0, 4, v31
	s_or_b32 s6, s6, s12
	v_lshl_add_u64 v[156:157], v[4:5], 0, v[0:1]
	v_add_u32_e32 v4, s6, v38
	s_load_dwordx2 s[6:7], s[96:97], 0x140
	v_lshl_add_u64 v[158:159], v[2:3], 0, v[0:1]
	v_mul_u32_u24_e32 v31, 0x41, v31
	v_lshlrev_b32_e32 v39, 3, v42
	v_add_lshl_u32 v31, v31, v38, 4
	s_waitcnt lgkmcnt(0)
	v_mov_b64_e32 v[2:3], s[6:7]
	v_mad_i64_i32 v[2:3], s[6:7], v4, s48, v[2:3]
	s_lshl_b32 s6, s8, 2
	s_or_b32 s6, s6, 3
	s_cmp_lt_u32 s8, 32
	s_cselect_b32 s13, s6, 0x80
	s_lshl_b32 s74, s13, 6
	s_lshl_b64 s[6:7], s[74:75], 11
	v_lshl_add_u64 v[160:161], v[2:3], 0, v[0:1]
	v_lshl_add_u64 v[6:7], v[156:157], 0, s[6:7]
	s_lshl_b64 s[6:7], s[74:75], 7
	s_mov_b64 s[8:9], 0x100800
	s_waitcnt vmcnt(0)
	v_lshl_add_u64 v[10:11], v[158:159], 0, s[6:7]
	s_lshl_b64 s[6:7], s[74:75], 1
	v_lshl_add_u64 v[162:163], v[160:161], 0, s[8:9]
	v_lshl_add_u64 v[14:15], v[160:161], 0, s[6:7]
	v_lshl_add_u64 v[18:19], v[162:163], 0, s[6:7]
	global_load_dwordx4 v[2:5], v[6:7], off
	s_nop 0
	global_load_dwordx4 v[6:9], v[6:7], off offset:128
	s_nop 0
	global_load_dwordx4 v[10:13], v[10:11], off
	s_nop 0
	global_load_dwordx4 v[14:17], v[14:15], off
	s_nop 0
	global_load_dwordx4 v[32:35], v[18:19], off
	s_nop 0
	global_load_dwordx4 v[18:21], v[36:37], off
	global_load_dwordx4 v[22:25], v[36:37], off offset:32
	global_load_dwordx4 v[26:29], v[36:37], off offset:64
	global_load_dwordx4 v[96:99], v[36:37], off offset:96
	global_load_dwordx4 v[100:103], v[36:37], off offset:128
	global_load_dwordx4 v[104:107], v[36:37], off offset:160
	global_load_dwordx4 v[108:111], v[36:37], off offset:192
	global_load_dwordx4 v[112:115], v[36:37], off offset:224
	global_load_dwordx4 v[116:119], v[36:37], off offset:256
	global_load_dwordx4 v[120:123], v[36:37], off offset:288
	global_load_dwordx4 v[124:127], v[36:37], off offset:320
	global_load_dwordx4 v[128:131], v[36:37], off offset:352
	s_sub_i32 s6, s74, 64
	s_mov_b32 s7, s75
	s_lshl_b64 s[8:9], s[6:7], 11
	v_lshl_add_u64 v[36:37], v[156:157], 0, s[8:9]
	s_lshl_b64 s[8:9], s[6:7], 7
	s_barrier
	global_load_dwordx4 v[132:135], v[36:37], off
	global_load_dwordx4 v[136:139], v[36:37], off offset:128
	v_lshl_add_u64 v[36:37], v[158:159], 0, s[8:9]
	s_lshl_b64 s[6:7], s[6:7], 1
	global_load_dwordx4 v[140:143], v[36:37], off
	v_lshl_add_u64 v[36:37], v[160:161], 0, s[6:7]
	v_lshl_add_u64 v[40:41], v[162:163], 0, s[6:7]
	global_load_dwordx4 v[144:147], v[36:37], off
	global_load_dwordx4 v[148:151], v[40:41], off
	s_movk_i32 s8, 0x90
	v_and_b32_e32 v164, 0x60, v0
	v_and_b32_e32 v165, 16, v0
	v_lshrrev_b32_e32 v165, 1, v165
	v_or_b32_e32 v164, v164, v165
	v_mad_u32_u24 v164, v38, s8, v164
	v_add_u32_e32 v0, 0x6180, v164
	v_add_u32_e32 v36, 0x8580, v164
	v_mul_u32_u24_e32 v168, 0x90, v43
	v_lshl_add_u32 v168, v42, 4, v168
	s_movk_i32 s8, 0x41
	v_lshlrev_b32_e32 v165, 2, v42
	s_movk_i32 s6, 0x2010
	v_or_b32_e32 v167, 31, v166
	v_cmp_gt_i32_e64 s[6:7], s6, v166
	s_or_b32 s14, s74, 63
	s_mov_b32 s15, 0
	v_mov_b32_e32 v217, 0xf149f2ca
	v_mov_b32_e32 v216, 0
	s_waitcnt vmcnt(21)
	ds_write_b128 v31, v[2:5]
	s_waitcnt vmcnt(20)
	ds_write_b128 v31, v[6:9] offset:8320
	s_waitcnt vmcnt(19)
	ds_write_b128 v31, v[10:13] offset:16640
	s_waitcnt vmcnt(18)
	ds_write2_b64 v0, v[14:15], v[16:17] offset1:2
	s_waitcnt vmcnt(17)
; template <int MODE> ...
;     ...
; #pragma unroll
;   for (int mb = 0; mb < 4; ++mb)
; #pragma unroll
;     for (int i = 0; i < 16; ++i) O[mb][i] = 0.f;
;   float m_run = -1e30f, l_run = 0.f, carry = 0.f;
;   const int c8 = tid & 7, kr_ = tid >> 3;
;   const int vc = tid & 7, vd = tid >> 3;
;   const bf16_t* k1p = K1g + ((size_t)b * LP + kr_) * 1024 + h * 128 + c8 * 8;
;   const bf16_t* k2p = K2g + ((size_t)b * LP + kr_) * 64 + c8 * 8;
;   const bf16_t* vp0 = VTg + ((size_t)(b * 8 + h) * 128 + vd) * LP + vc * 8;
;   const int ks_off = (c8 * 65 + kr_) * 16;
;   const int vs_off = vd * 136 + vc * 16;
;   uint4 k0, k1, k2, v0, v1;
;   k2 = make_uint4(0u, 0u, 0u, 0u);
;     ...
;   const int kt_hi = (4 * qt + 3 < (L - 1) / 64) ? (4 * qt + 3) : ((L - 1) / 64);
;   LOAD_KV(kt_hi);
;   __syncthreads();
;   STORE_KV(0);
;   LOAD_KV(kt_hi - 1);
;   __syncthreads();
;   int vcur = 0;
;   f32x16 S;
; #pragma unroll
;   for (int i = 0; i < 16; ++i) S[i] = 0.f;
;     ...
;         const char* vbase = Vs + vcur * VSZ + ql * 136 + g * 8 + sub * 64;
; #pragma unroll
;         for (int hh = 0; hh < 2; ++hh) {
;           union { bf16x8 v; unsigned u[4]; } pf;
; #pragma unroll
;           for (int j = 0; j < 4; ++j) pf.u[j] = pk2(S[8 * hh + 2 * j], S[8 * hh + 2 * j + 1]);
; #pragma unroll
;           for (int mb = 0; mb < 4; ++mb) {
;             const char* vp = vbase + mb * 32 * 136 + hh * 32;
;             const uint2 lo = *reinterpret_cast<const uint2*>(vp);
;             const uint2 hi = *reinterpret_cast<const uint2*>(vp + 16);
;             union { bf16x8 v; unsigned u[4]; } vf;
;             vf.u[0] = lo.x; vf.u[1] = lo.y; vf.u[2] = hi.x; vf.u[3] = hi.y;
;             O[mb] = __builtin_amdgcn_mfma_f32_32x32x16_bf16(vf.v, pf.v, O[mb], 0, 0, 0);
;           }
;         }
	ds_write2_b64 v36, v[32:33], v[34:35] offset1:2
	v_mov_b32_e32 v3, 0x82
	v_mov_b32_e32 v4, 0x104
	v_mov_b32_e32 v5, 0x186
	v_mov_b32_e32 v6, 0x208
	v_mov_b32_e32 v7, 0x28a
	v_mov_b32_e32 v8, 0x30c
	v_mov_b32_e32 v9, 0x38e
	v_mov_b32_e32 v10, 0x410
	v_mov_b32_e32 v11, 0x492
	v_mov_b32_e32 v12, 0x514
	v_mov_b32_e32 v13, 0x596
	v_or_b32_e32 v0, 32, v43
	v_mul_u32_u24_e32 v2, 0x41, v42
	v_mad_u32_u24 v3, v42, s8, v3
	v_mad_u32_u24 v4, v42, s8, v4
	v_mad_u32_u24 v5, v42, s8, v5
	v_mad_u32_u24 v6, v42, s8, v6
	v_mad_u32_u24 v7, v42, s8, v7
	v_mad_u32_u24 v8, v42, s8, v8
	v_mad_u32_u24 v9, v42, s8, v9
	v_mad_u32_u24 v10, v42, s8, v10
	v_mad_u32_u24 v11, v42, s8, v11
	v_mad_u32_u24 v12, v42, s8, v12
	v_mad_u32_u24 v13, v42, s8, v13
	v_mov_b32_e32 v14, v1
	v_mov_b32_e32 v15, v1
	v_add_lshl_u32 v169, v2, v0, 4
	v_add_lshl_u32 v170, v3, v0, 4
	v_add_lshl_u32 v171, v4, v0, 4
	v_add_lshl_u32 v172, v5, v0, 4
	v_add_lshl_u32 v173, v6, v0, 4
	v_add_lshl_u32 v174, v7, v0, 4
	v_add_lshl_u32 v175, v8, v0, 4
	v_add_lshl_u32 v176, v9, v0, 4
	v_add_lshl_u32 v177, v10, v0, 4
	v_add_lshl_u32 v178, v11, v0, 4
	v_add_lshl_u32 v179, v12, v0, 4
	v_add_lshl_u32 v203, v13, v0, 4
	v_add_lshl_u32 v204, v2, v43, 4
	v_add_lshl_u32 v205, v3, v43, 4
	v_add_lshl_u32 v206, v4, v43, 4
	v_add_lshl_u32 v207, v5, v43, 4
	v_add_lshl_u32 v208, v6, v43, 4
	v_add_lshl_u32 v209, v7, v43, 4
	v_add_lshl_u32 v210, v8, v43, 4
	v_add_lshl_u32 v211, v9, v43, 4
	v_add_lshl_u32 v212, v10, v43, 4
	v_add_lshl_u32 v213, v11, v43, 4
	v_add_lshl_u32 v214, v12, v43, 4
	v_add_lshl_u32 v215, v13, v43, 4
	v_mov_b32_e32 v0, v1
	v_mov_b32_e32 v2, v1
	v_mov_b32_e32 v3, v1
	v_mov_b32_e32 v4, v1
	v_mov_b32_e32 v5, v1
	v_mov_b32_e32 v6, v1
	v_mov_b32_e32 v7, v1
	v_mov_b32_e32 v8, v1
	v_mov_b32_e32 v9, v1
	v_mov_b32_e32 v10, v1
	v_mov_b32_e32 v11, v1
	v_mov_b32_e32 v12, v1
	v_mov_b32_e32 v13, v1
	v_mov_b64_e32 v[46:47], v[14:15]
	v_mov_b64_e32 v[62:63], v[14:15]
	v_mov_b64_e32 v[78:79], v[14:15]
	v_mov_b64_e32 v[94:95], v[14:15]
	v_mov_b64_e32 v[44:45], v[12:13]
	v_mov_b64_e32 v[42:43], v[10:11]
	v_mov_b64_e32 v[40:41], v[8:9]
	v_mov_b64_e32 v[38:39], v[6:7]
	v_mov_b64_e32 v[36:37], v[4:5]
	v_mov_b64_e32 v[34:35], v[2:3]
	v_mov_b64_e32 v[32:33], v[0:1]
	v_mov_b64_e32 v[60:61], v[12:13]
	v_mov_b64_e32 v[58:59], v[10:11]
	v_mov_b64_e32 v[56:57], v[8:9]
	v_mov_b64_e32 v[54:55], v[6:7]
	v_mov_b64_e32 v[52:53], v[4:5]
	v_mov_b64_e32 v[50:51], v[2:3]
	v_mov_b64_e32 v[48:49], v[0:1]
	v_mov_b64_e32 v[76:77], v[12:13]
	v_mov_b64_e32 v[74:75], v[10:11]
	v_mov_b64_e32 v[72:73], v[8:9]
	v_mov_b64_e32 v[70:71], v[6:7]
	v_mov_b64_e32 v[68:69], v[4:5]
	v_mov_b64_e32 v[66:67], v[2:3]
	v_mov_b64_e32 v[64:65], v[0:1]
	v_mov_b64_e32 v[92:93], v[12:13]
	v_mov_b64_e32 v[90:91], v[10:11]
	v_mov_b64_e32 v[88:89], v[8:9]
	v_mov_b64_e32 v[86:87], v[6:7]
	v_mov_b64_e32 v[84:85], v[4:5]
	v_mov_b64_e32 v[82:83], v[2:3]
	v_mov_b64_e32 v[80:81], v[0:1]
	v_mov_b64_e32 v[16:17], v[14:15]
	v_mov_b64_e32 v[14:15], v[12:13]
	v_mov_b64_e32 v[12:13], v[10:11]
	v_mov_b64_e32 v[10:11], v[8:9]
	v_mov_b64_e32 v[8:9], v[6:7]
	v_mov_b64_e32 v[6:7], v[4:5]
	v_mov_b64_e32 v[4:5], v[2:3]
	v_mov_b64_e32 v[2:3], v[0:1]
	s_waitcnt lgkmcnt(0)
	s_barrier
	s_branch .LBB0_350
.LBB0_348:
	v_add_u32_e32 v187, s16, v168
	ds_read_b128 v[218:221], v187 offset:24960
	ds_read_b128 v[222:225], v187 offset:29568
	ds_read_b128 v[226:229], v187 offset:34176
	ds_read_b128 v[230:233], v187 offset:38784
	ds_read_b128 v[234:237], v187 offset:24992
	ds_read_b128 v[238:241], v187 offset:29600
	ds_read_b128 v[242:245], v187 offset:34208
	ds_read_b128 v[246:249], v187 offset:38816
	v_sub_f32_e32 v0, v2, v217
	v_exp_f32_e32 v2, v0
	v_sub_f32_e32 v0, v3, v217
	v_exp_f32_e32 v3, v0
	v_sub_f32_e32 v0, v4, v217
	v_exp_f32_e32 v4, v0
	v_sub_f32_e32 v0, v5, v217
	v_exp_f32_e32 v5, v0
	v_sub_f32_e32 v0, v6, v217
	v_exp_f32_e32 v6, v0
	v_sub_f32_e32 v0, v7, v217
	v_exp_f32_e32 v7, v0
	v_sub_f32_e32 v8, v8, v217
	v_sub_f32_e32 v9, v9, v217
	v_exp_f32_e32 v8, v8
	v_exp_f32_e32 v9, v9
	v_cvt_pk_bf16_f32 v194, v2, v3
	v_cvt_pk_bf16_f32 v195, v4, v5
	v_cvt_pk_bf16_f32 v196, v6, v7
	v_cvt_pk_bf16_f32 v197, v8, v9
	s_waitcnt lgkmcnt(7)
	v_mfma_f32_32x32x16_bf16 v[80:95], v[218:221], v[194:197], v[80:95]
	v_sub_f32_e32 v10, v10, v217
	v_sub_f32_e32 v11, v11, v217
	v_sub_f32_e32 v12, v12, v217
	v_sub_f32_e32 v13, v13, v217
	s_waitcnt lgkmcnt(6)
	v_mfma_f32_32x32x16_bf16 v[64:79], v[222:225], v[194:197], v[64:79]
	v_sub_f32_e32 v14, v14, v217
	v_sub_f32_e32 v15, v15, v217
	v_sub_f32_e32 v16, v16, v217
	v_sub_f32_e32 v17, v17, v217
	v_exp_f32_e32 v10, v10
	v_exp_f32_e32 v11, v11
	s_waitcnt lgkmcnt(5)
	v_mfma_f32_32x32x16_bf16 v[48:63], v[226:229], v[194:197], v[48:63]
	v_exp_f32_e32 v12, v12
	v_exp_f32_e32 v13, v13
	v_exp_f32_e32 v14, v14
	v_exp_f32_e32 v15, v15
	v_exp_f32_e32 v16, v16
	v_exp_f32_e32 v17, v17
	s_waitcnt lgkmcnt(4)
	v_mfma_f32_32x32x16_bf16 v[32:47], v[230:233], v[194:197], v[32:47]
	v_cvt_pk_bf16_f32 v190, v10, v11
	v_cvt_pk_bf16_f32 v191, v12, v13
	v_cvt_pk_bf16_f32 v192, v14, v15
	v_cvt_pk_bf16_f32 v193, v16, v17
	v_add_f32_e32 v180, 0, v2
	v_add_f32_e32 v180, v3, v180
	s_waitcnt lgkmcnt(3)
	v_mfma_f32_32x32x16_bf16 v[80:95], v[234:237], v[190:193], v[80:95]
	v_add_f32_e32 v180, v4, v180
	v_add_f32_e32 v180, v5, v180
	v_add_f32_e32 v180, v6, v180
	v_add_f32_e32 v180, v7, v180
	v_add_f32_e32 v180, v8, v180
	v_add_f32_e32 v180, v9, v180
	s_waitcnt lgkmcnt(2)
	v_mfma_f32_32x32x16_bf16 v[64:79], v[238:241], v[190:193], v[64:79]
	v_add_f32_e32 v180, v10, v180
	v_add_f32_e32 v0, v11, v180
	v_add_f32_e32 v0, v12, v0
	v_add_f32_e32 v0, v13, v0
	v_add_f32_e32 v0, v14, v0
	v_add_f32_e32 v0, v15, v0
	s_waitcnt lgkmcnt(1)
	v_mfma_f32_32x32x16_bf16 v[48:63], v[242:245], v[190:193], v[48:63]
	v_add_f32_e32 v0, v16, v0
	v_add_f32_e32 v0, v17, v0
	v_add_f32_e32 v216, v216, v0
	s_waitcnt lgkmcnt(0)
	v_mfma_f32_32x32x16_bf16 v[32:47], v[246:249], v[190:193], v[32:47]

; template <int MODE> ...
;     ...
;         const int kbase = k32 + 4 * g;
;         if (MODE == 0) {
;           const bool diag = (k32 + 31) > w_first;
;           float mx = -1e30f;
;           if (diag) {
; #pragma unroll
;             for (int i = 0; i < 16; ++i) {
;               const int key = kbase + 8 * (i >> 2) + (i & 3);
;               const float sv = (key <= t_q) ? S[i] : -1e30f;
;               S[i] = sv;
;               mx = fmaxf(mx, sv);
;             }
;           } else {
; #pragma unroll
;             for (int i = 0; i < 16; ++i) mx = fmaxf(mx, S[i]);
;           }
;           mx = fmaxf(mx, __shfl_xor(mx, 32));
.LBB0_352:
	s_or_b64 exec, exec, s[8:9]
	s_mul_i32 s16, s15, 0x4800
	s_and_saveexec_b64 s[8:9], s[10:11]
	s_cbranch_execz .LBB0_360
	v_cmp_le_u32_e32 vcc, s14, v166
	s_and_saveexec_b64 s[10:11], vcc
	s_xor_b64 s[10:11], exec, s[10:11]
	s_mov_b32 s17, 0xf149f2ca
	s_nop 3
	v_max3_f32 v0, v2, s17, v3
	v_max3_f32 v0, v0, v4, v5
	v_max3_f32 v0, v0, v6, v7
	v_max3_f32 v0, v0, v8, v9
	v_max3_f32 v0, v0, v10, v11
	v_max3_f32 v0, v0, v12, v13
	v_max3_f32 v0, v0, v14, v15
	v_max3_f32 v0, v0, v16, v17
	s_andn2_saveexec_b64 s[10:11], s[10:11]
	s_cbranch_execz .LBB0_357
	v_add_u32_e32 v0, s14, v165
	v_subrev_u32_e32 v180, 31, v0
	v_cmp_le_i32_e32 vcc, v180, v30
	v_subrev_u32_e32 v181, 29, v0
	s_mov_b32 s17, 0xf149f2ca
	v_cndmask_b32_e32 v2, v202, v2, vcc
	v_cmp_lt_i32_e32 vcc, v180, v30
	s_nop 1
	v_cndmask_b32_e32 v3, v202, v3, vcc
	v_cmp_le_i32_e32 vcc, v181, v30
	v_subrev_u32_e32 v181, 28, v0
	v_max3_f32 v180, v2, s17, v3
	v_cndmask_b32_e32 v4, v202, v4, vcc
	v_cmp_le_i32_e32 vcc, v181, v30
	v_subrev_u32_e32 v181, 23, v0
	s_nop 0
	v_cndmask_b32_e32 v5, v202, v5, vcc
	v_cmp_le_i32_e32 vcc, v181, v30
	v_subrev_u32_e32 v181, 22, v0
	v_max3_f32 v180, v180, v4, v5
	v_cndmask_b32_e32 v6, v202, v6, vcc
	v_cmp_le_i32_e32 vcc, v181, v30
	v_subrev_u32_e32 v181, 21, v0
	s_nop 0
	v_cndmask_b32_e32 v7, v202, v7, vcc
	v_cmp_le_i32_e32 vcc, v181, v30
	v_subrev_u32_e32 v181, 20, v0
	v_max3_f32 v180, v180, v6, v7
	v_cndmask_b32_e32 v8, v202, v8, vcc
	v_cmp_le_i32_e32 vcc, v181, v30
	v_add_u32_e32 v181, -15, v0
	s_nop 0
	v_cndmask_b32_e32 v9, v202, v9, vcc
	v_cmp_le_i32_e32 vcc, v181, v30
	v_add_u32_e32 v181, -14, v0
	v_max3_f32 v180, v180, v8, v9
	v_cndmask_b32_e32 v10, v202, v10, vcc
	v_cmp_le_i32_e32 vcc, v181, v30
	v_add_u32_e32 v181, -13, v0
	s_nop 0
	v_cndmask_b32_e32 v11, v202, v11, vcc
	v_cmp_le_i32_e32 vcc, v181, v30
	v_add_u32_e32 v181, -12, v0
	v_max3_f32 v180, v180, v10, v11
	v_cndmask_b32_e32 v12, v202, v12, vcc
	v_cmp_le_i32_e32 vcc, v181, v30
	v_add_u32_e32 v181, -7, v0
	s_nop 0
	v_cndmask_b32_e32 v13, v202, v13, vcc
	v_cmp_le_i32_e32 vcc, v181, v30
	v_add_u32_e32 v181, -6, v0
	v_max3_f32 v180, v180, v12, v13
	v_cndmask_b32_e32 v14, v202, v14, vcc
	v_cmp_le_i32_e32 vcc, v181, v30
	v_add_u32_e32 v181, -5, v0
	v_add_u32_e32 v0, -4, v0
	v_cndmask_b32_e32 v15, v202, v15, vcc
	v_cmp_le_i32_e32 vcc, v181, v30
	v_max3_f32 v180, v180, v14, v15
	s_nop 0
	v_cndmask_b32_e32 v16, v202, v16, vcc
	v_cmp_le_i32_e32 vcc, v0, v30
	s_nop 1
	v_cndmask_b32_e32 v17, v202, v17, vcc
	v_max3_f32 v0, v180, v16, v17

; template <int MODE> ...
;     ...
;           float lsum = 0.f;
; #pragma unroll
;           for (int i = 0; i < 16; ++i) {
;             const float pv = __builtin_amdgcn_exp2f(S[i] - m_run);
;             S[i] = pv;
;             lsum += pv;
;           }
;           l_run += lsum;
;         } else {
;           float gs[4], gp[4], suf[4];
; #pragma unroll
;           for (int m = 0; m < 4; ++m) {
;             float acc4 = 0.f;
; #pragma unroll
;             for (int e2 = 0; e2 < 4; ++e2) {
;               const int key = kbase + 8 * m + e2;
;               const float lg = S[4 * m + e2];
;               const float sp = fmaxf(lg, 0.f) + __logf(1.f + __expf(-fabsf(lg)));
;               acc4 += (key < t_q) ? -sp : 0.f;
;             }
;             gs[m] = acc4;
;           }
; #pragma unroll
;           for (int m = 0; m < 4; ++m) gp[m] = __shfl_xor(gs[m], 32);
;           float run = 0.f;
; #pragma unroll
;           for (int m = 3; m >= 0; --m) {
;             suf[m] = run + ((g == 0) ? gp[m] : 0.f);
;             run += gs[m] + gp[m];
;           }
; #pragma unroll
;           for (int m = 0; m < 4; ++m) {
;             float later = carry + suf[m];
; #pragma unroll
;     ...
;               const int key = kbase + 8 * m + e2;
;               const bool ok = key < t_q;
;               const float lg = S[4 * m + e2];
;               const float sp = fmaxf(lg, 0.f) + __logf(1.f + __expf(-fabsf(lg)));
;               S[4 * m + e2] = ok ? __expf((lg - sp) + later) : 0.f;
;               later += ok ? -sp : 0.f;
;             }
;           }
;           carry += run;
;         }
;         const char* vbase = Vs + vcur * VSZ + ql * 136 + g * 8 + sub * 64;
; #pragma unroll
;         for (int hh = 0; hh < 2; ++hh) {
;           union { bf16x8 v; unsigned u[4]; } pf;
; #pragma unroll
;           for (int j = 0; j < 4; ++j) pf.u[j] = pk2(S[8 * hh + 2 * j], S[8 * hh + 2 * j + 1]);
; #pragma unroll
;           for (int mb = 0; mb < 4; ++mb) {
;             const char* vp = vbase + mb * 32 * 136 + hh * 32;
;             const uint2 lo = *reinterpret_cast<const uint2*>(vp);
;             const uint2 hi = *reinterpret_cast<const uint2*>(vp + 16);
;             union { bf16x8 v; unsigned u[4]; } vf;
;             vf.u[0] = lo.x; vf.u[1] = lo.y; vf.u[2] = hi.x; vf.u[3] = hi.y;
;             O[mb] = __builtin_amdgcn_mfma_f32_32x32x16_bf16(vf.v, pf.v, O[mb], 0, 0, 0);
;           }
.LBB0_359:
	v_add_u32_e32 v187, s16, v168
	ds_read_b128 v[218:221], v187 offset:25024
	ds_read_b128 v[222:225], v187 offset:29632
	ds_read_b128 v[226:229], v187 offset:34240
	ds_read_b128 v[230:233], v187 offset:38848
	ds_read_b128 v[234:237], v187 offset:25056
	ds_read_b128 v[238:241], v187 offset:29664
	ds_read_b128 v[242:245], v187 offset:34272
	ds_read_b128 v[246:249], v187 offset:38880
	v_sub_f32_e32 v0, v2, v217
	v_exp_f32_e32 v2, v0
	v_sub_f32_e32 v0, v3, v217
	v_exp_f32_e32 v3, v0
	v_sub_f32_e32 v0, v4, v217
	v_exp_f32_e32 v4, v0
	v_sub_f32_e32 v0, v5, v217
	v_exp_f32_e32 v5, v0
	v_sub_f32_e32 v0, v6, v217
	v_exp_f32_e32 v6, v0
	v_sub_f32_e32 v0, v7, v217
	v_exp_f32_e32 v7, v0
	v_sub_f32_e32 v8, v8, v217
	v_sub_f32_e32 v9, v9, v217
	v_exp_f32_e32 v8, v8
	v_exp_f32_e32 v9, v9
	v_cvt_pk_bf16_f32 v194, v2, v3
	v_cvt_pk_bf16_f32 v195, v4, v5
	v_cvt_pk_bf16_f32 v196, v6, v7
	v_cvt_pk_bf16_f32 v197, v8, v9
	s_waitcnt lgkmcnt(7)
	v_mfma_f32_32x32x16_bf16 v[80:95], v[218:221], v[194:197], v[80:95]
	v_sub_f32_e32 v10, v10, v217
	v_sub_f32_e32 v11, v11, v217
	v_sub_f32_e32 v12, v12, v217
	v_sub_f32_e32 v13, v13, v217
	s_waitcnt lgkmcnt(6)
	v_mfma_f32_32x32x16_bf16 v[64:79], v[222:225], v[194:197], v[64:79]
	v_sub_f32_e32 v14, v14, v217
	v_sub_f32_e32 v15, v15, v217
	v_sub_f32_e32 v16, v16, v217
	v_sub_f32_e32 v17, v17, v217
	v_exp_f32_e32 v10, v10
	v_exp_f32_e32 v11, v11
	s_waitcnt lgkmcnt(5)
	v_mfma_f32_32x32x16_bf16 v[48:63], v[226:229], v[194:197], v[48:63]
	v_exp_f32_e32 v12, v12
	v_exp_f32_e32 v13, v13
	v_exp_f32_e32 v14, v14
	v_exp_f32_e32 v15, v15
	v_exp_f32_e32 v16, v16
	v_exp_f32_e32 v17, v17
	s_waitcnt lgkmcnt(4)
	v_mfma_f32_32x32x16_bf16 v[32:47], v[230:233], v[194:197], v[32:47]
	v_cvt_pk_bf16_f32 v190, v10, v11
	v_cvt_pk_bf16_f32 v191, v12, v13
	v_cvt_pk_bf16_f32 v192, v14, v15
	v_cvt_pk_bf16_f32 v193, v16, v17
	v_add_f32_e32 v180, 0, v2
	v_add_f32_e32 v180, v3, v180
	s_waitcnt lgkmcnt(3)
	v_mfma_f32_32x32x16_bf16 v[80:95], v[234:237], v[190:193], v[80:95]
	v_add_f32_e32 v180, v4, v180
	v_add_f32_e32 v180, v5, v180
	v_add_f32_e32 v180, v6, v180
	v_add_f32_e32 v180, v7, v180
	v_add_f32_e32 v180, v8, v180
	v_add_f32_e32 v180, v9, v180
	s_waitcnt lgkmcnt(2)
	v_mfma_f32_32x32x16_bf16 v[64:79], v[238:241], v[190:193], v[64:79]
	v_add_f32_e32 v180, v10, v180
	v_add_f32_e32 v0, v11, v180
	v_add_f32_e32 v0, v12, v0
	v_add_f32_e32 v0, v13, v0
	v_add_f32_e32 v0, v14, v0
	v_add_f32_e32 v0, v15, v0
	s_waitcnt lgkmcnt(1)
	v_mfma_f32_32x32x16_bf16 v[48:63], v[242:245], v[190:193], v[48:63]
	v_add_f32_e32 v0, v16, v0
	v_add_f32_e32 v0, v17, v0
	v_add_f32_e32 v216, v216, v0
	s_waitcnt lgkmcnt(0)
	v_mfma_f32_32x32x16_bf16 v[32:47], v[246:249], v[190:193], v[32:47]

; template <int MODE> ...
;     ...
;       if (sub == 0) {
;         __syncthreads();
;         if (has_next) STORE_KV(vcur ^ 1);
;         if (kt > 1) LOAD_KV(kt - 2);
.LBB0_362:
	s_or_b64 exec, exec, s[8:9]
	s_xor_b32 s15, s15, 1
	s_cmp_eq_u32 s13, 0
	s_barrier
	s_cbranch_scc1 .LBB0_364
	s_mul_i32 s8, s15, 0x4800
	v_add_u32_e32 v0, s8, v164
	v_add_u32_e32 v180, 0x6180, v0
	v_add_u32_e32 v0, 0x8580, v0
	s_waitcnt vmcnt(4)
	ds_write_b128 v31, v[132:135]
	s_waitcnt vmcnt(3)
	ds_write_b128 v31, v[136:139] offset:8320
	s_waitcnt vmcnt(2)
	ds_write_b128 v31, v[140:143] offset:16640
	s_waitcnt vmcnt(1)
	ds_write2_b64 v180, v[144:145], v[146:147] offset1:2
	s_waitcnt vmcnt(0)
	ds_write2_b64 v0, v[148:149], v[150:151] offset1:2
